# NSA compressed-branch K/V fragments staged through LDS tile buffers (4 coalesced loads per thread instead of 48 per-lane fragment loads)
# speedup vs baseline: 1.0331x; 1.0134x over previous
.LBB0_64:
	s_and_b64 s[0:1], s[30:31], exec
	v_readlane_b32 s0, v255, 24
	v_readlane_b32 s1, v255, 25
	s_cselect_b32 s2, s1, s0
	s_and_b32 s0, s3, 3
	s_ashr_i32 s29, s8, 8
	v_readlane_b32 s1, v255, 27
	s_or_b32 s13, s0, s1
	s_lshl_b32 s0, s2, 6
	s_lshl_b32 s33, s29, 5
	v_and_b32_e32 v193, 31, v212
	s_add_i32 s0, s33, s0
	s_waitcnt vmcnt(0)
	v_or_b32_e32 v94, s0, v193
	s_add_u32 s0, s18, s25
	s_addc_u32 s1, s19, s9
	s_add_u32 s22, s0, 0x5400000
	v_ashrrev_i32_e32 v95, 31, v94
	s_addc_u32 s23, s1, 0
	s_lshl_b32 s6, s13, 11
	v_lshlrev_b64 v[4:5], 7, v[94:95]
	v_lshl_add_u64 v[2:3], s[6:7], 0, v[94:95]
	v_lshl_add_u64 v[4:5], s[22:23], 0, v[4:5]
	s_mul_i32 s6, s13, 12
	v_lshl_add_u64 v[4:5], v[4:5], 0, s[6:7]
	s_mov_b32 s0, 0x1300000
	v_add_co_u32_e32 v4, vcc, s0, v4
	v_readlane_b32 s0, v255, 28
	v_bfe_u32 v213, v212, 5, 1
	v_lshlrev_b64 v[2:3], 7, v[2:3]
	s_lshl_b32 s6, s0, 1
	v_lshl_add_u64 v[2:3], s[22:23], 0, v[2:3]
	v_lshlrev_b32_e32 v0, 4, v213
	s_add_u32 s0, s22, s6
	v_lshlrev_b32_e32 v194, 3, v212
	v_ashrrev_i32_e32 v210, 3, v212
	v_lshl_add_u64 v[2:3], v[2:3], 0, v[0:1]
	v_addc_co_u32_e32 v5, vcc, 0, v5, vcc
	s_addc_u32 s1, s23, 0
	v_ashrrev_i32_e32 v195, 31, v194
	v_ashrrev_i32_e32 v211, 31, v210
	global_load_dwordx4 v[86:89], v[2:3], off offset:32
	global_load_dwordx4 v[82:85], v[2:3], off offset:64
	global_load_dwordx4 v[90:93], v[2:3], off offset:96
	global_load_dwordx3 v[190:192], v[4:5], off
	v_lshl_add_u64 v[4:5], v[194:195], 1, s[0:1]
	s_mov_b32 s4, 0x900000
	v_lshlrev_b64 v[196:197], 12, v[210:211]
	v_and_b32_e32 v8, 56, v194
	v_add_co_u32_e32 v4, vcc, s4, v4
	v_lshl_add_u64 v[6:7], s[0:1], 0, v[196:197]
	v_lshlrev_b32_e32 v208, 1, v8
	v_mov_b32_e32 v209, v1
	v_addc_co_u32_e32 v5, vcc, 0, v5, vcc
	v_lshl_add_u64 v[6:7], v[6:7], 0, v[208:209]
	s_mov_b32 s0, 0x980000
	v_add_co_u32_e32 v6, vcc, s0, v6
	s_add_u32 s0, s18, s20
	s_addc_u32 s1, s19, s21
	v_addc_co_u32_e32 v7, vcc, 0, v7, vcc
	global_load_dwordx4 v[106:109], v[4:5], off
	global_load_dwordx4 v[102:105], v[6:7], off
	v_lshl_add_u64 v[4:5], s[0:1], 0, v[0:1]
	v_lshlrev_b32_e32 v0, 7, v193
	v_lshl_add_u64 v[4:5], v[4:5], 0, v[0:1]
	s_mov_b64 s[0:1], 0x280000
	v_lshl_add_u64 v[34:35], v[4:5], 0, s[0:1]
	v_add_co_u32_e32 v4, vcc, 0x280000, v4
	s_cmp_gt_u32 s2, 7
	s_nop 0
	v_addc_co_u32_e32 v5, vcc, 0, v5, vcc
	global_load_dwordx4 v[98:101], v[2:3], off
	s_add_u32 s14, s18, s20
	s_addc_u32 s15, s19, s21
	s_add_u32 s14, s14, 0x280000
	s_addc_u32 s15, s15, 0
	s_add_u32 s16, s14, 0x40000
	s_addc_u32 s17, s15, 0
	v_lshlrev_b32_e32 v203, 4, v212
	v_add_u32_e32 v202, 0x2000, v203
	v_and_b32_e32 v248, 7, v212
	v_lshlrev_b32_e32 v251, 8, v210
	v_lshl_add_u32 v251, v248, 4, v251
	global_load_dwordx4 v[232:235], v203, s[14:15]
	global_load_dwordx4 v[236:239], v251, s[16:17]
	global_load_dwordx4 v[240:243], v202, s[14:15]
	global_load_dwordx4 v[244:247], v251, s[16:17] offset:128
	v_lshrrev_b32_e32 v249, 1, v210
	v_and_b32_e32 v249, 7, v249
	v_xor_b32_e32 v250, v248, v249
	v_lshlrev_b32_e32 v214, 7, v210
	v_lshl_add_u32 v250, v250, 4, v214
	v_and_b32_e32 v215, 6, v248
	v_xor_b32_e32 v215, v215, v249
	v_lshl_add_u32 v215, v215, 4, v214
	v_and_b32_e32 v216, 1, v248
	v_lshl_add_u32 v249, v216, 3, v215
	v_xor_b32_e32 v248, 16, v249
	v_add_u32_e32 v216, 0x4000, v250
	v_add_u32_e32 v217, 0x4000, v249
	v_add_u32_e32 v218, 0x4000, v248
	s_waitcnt vmcnt(0)
	ds_write_b128 v250, v[232:235] offset:49152
	ds_write_b64 v249, v[236:237] offset:57344
	ds_write_b64 v248, v[238:239] offset:57344
	ds_write_b128 v216, v[240:243] offset:49152
	ds_write_b64 v217, v[244:245] offset:57344
	ds_write_b64 v218, v[246:247] offset:57344
	v_lshrrev_b32_e32 v249, 1, v193
	v_and_b32_e32 v249, 7, v249
	v_xor_b32_e32 v249, v249, v213
	v_lshlrev_b32_e32 v250, 7, v193
	v_lshl_add_u32 v214, v249, 4, v250
	v_xor_b32_e32 v248, 2, v249
	v_lshl_add_u32 v215, v248, 4, v250
	v_xor_b32_e32 v248, 4, v249
	v_lshl_add_u32 v216, v248, 4, v250
	v_xor_b32_e32 v248, 6, v249
	v_lshl_add_u32 v217, v248, 4, v250
	v_add_u32_e32 v218, 0x4000, v214
	v_add_u32_e32 v219, 0x4000, v215
	v_add_u32_e32 v220, 0x4000, v216
	v_add_u32_e32 v221, 0x4000, v217
	s_waitcnt lgkmcnt(0)
	s_barrier
	s_cmp_gt_u32 s2, 7
	ds_read_b128 v[30:33], v214 offset:49152
	ds_read_b128 v[22:25], v215 offset:49152
	ds_read_b128 v[18:21], v216 offset:49152
	ds_read_b128 v[26:29], v217 offset:49152
	s_cselect_b64 s[36:37], -1, 0
	s_cmp_lt_u32 s2, 8
	s_cbranch_scc1 .LBB0_66
	v_add_co_u32_e32 v14, vcc, 0x1000, v34
	s_nop 1
	v_addc_co_u32_e32 v15, vcc, 0, v35, vcc
	ds_read_b128 v[2:5], v214 offset:53248
	ds_read_b128 v[6:9], v215 offset:53248
	ds_read_b128 v[10:13], v216 offset:53248
	s_nop 0
	ds_read_b128 v[14:17], v217 offset:53248
.LBB0_66:
	s_cmp_gt_u32 s2, 15
	s_cselect_b64 s[4:5], -1, 0
	s_cmp_lt_u32 s2, 16
	s_cbranch_scc1 .LBB0_68
	v_add_co_u32_e32 v36, vcc, 0x2000, v34
	s_nop 1
	v_addc_co_u32_e32 v37, vcc, 0, v35, vcc
	ds_read_b128 v[78:81], v218 offset:49152
	ds_read_b128 v[162:165], v219 offset:49152
	ds_read_b128 v[166:169], v220 offset:49152
	ds_read_b128 v[170:173], v221 offset:49152
.LBB0_68:
	s_and_b32 s38, s2, 24
	s_cmp_eq_u32 s38, 24
	s_cselect_b64 s[0:1], -1, 0
	s_cmp_lg_u32 s38, 24
	s_cbranch_scc1 .LBB0_70
	v_add_co_u32_e32 v34, vcc, 0x3000, v34
	s_nop 1
	v_addc_co_u32_e32 v35, vcc, 0, v35, vcc
	ds_read_b128 v[174:177], v218 offset:53248
	ds_read_b128 v[178:181], v219 offset:53248
	ds_read_b128 v[182:185], v220 offset:53248
	ds_read_b128 v[186:189], v221 offset:53248
.LBB0_70:
	s_add_u32 s38, s18, s20
	s_addc_u32 s39, s19, s21
	v_lshlrev_b32_e32 v34, 8, v193
	v_mov_b32_e32 v35, v1
	v_lshl_add_u64 v[34:35], s[38:39], 0, v[34:35]
	v_lshlrev_b32_e32 v36, 3, v213
	v_mov_b32_e32 v37, v1
	v_lshl_add_u64 v[36:37], v[34:35], 0, v[36:37]
	s_mov_b64 s[38:39], 0x2c0000
	v_lshl_add_u64 v[34:35], v[36:37], 0, s[38:39]
	s_mov_b32 s38, 0x2c0000
	v_add_co_u32_e32 v38, vcc, s38, v36
	s_nop 1
	v_addc_co_u32_e32 v39, vcc, 0, v37, vcc
	v_add_co_u32_e32 v36, vcc, 0x2c2000, v36
	ds_read_b128 v[74:77], v214 offset:57344
	ds_read_b128 v[70:73], v215 offset:57344
	v_addc_co_u32_e32 v37, vcc, 0, v37, vcc
	ds_read_b128 v[66:69], v214 offset:61440
	ds_read_b128 v[158:161], v215 offset:61440
	v_cndmask_b32_e64 v36, 0, 1, s[36:37]
	v_cmp_ne_u32_e64 s[42:43], 1, v36
	s_andn2_b64 vcc, exec, s[36:37]
	s_cbranch_vccnz .LBB0_72
	v_add_co_u32_e32 v36, vcc, 0x2000, v34
	ds_read_b128 v[146:149], v216 offset:57344
	ds_read_b128 v[142:145], v217 offset:57344
	v_addc_co_u32_e32 v37, vcc, 0, v35, vcc
	ds_read_b128 v[154:157], v216 offset:61440
	ds_read_b128 v[150:153], v217 offset:61440
.LBB0_72:
	v_cndmask_b32_e64 v36, 0, 1, s[4:5]
	v_cmp_ne_u32_e64 s[40:41], 1, v36
	s_andn2_b64 vcc, exec, s[4:5]
	s_cbranch_vccnz .LBB0_74
	v_add_co_u32_e32 v36, vcc, 0x2000, v34
	ds_read_b128 v[130:133], v218 offset:57344
	ds_read_b128 v[126:129], v219 offset:57344
	v_addc_co_u32_e32 v37, vcc, 0, v35, vcc
	ds_read_b128 v[138:141], v218 offset:61440
	ds_read_b128 v[134:137], v219 offset:61440
.LBB0_74:
	v_cndmask_b32_e64 v36, 0, 1, s[0:1]
	v_cmp_ne_u32_e64 s[38:39], 1, v36
	s_andn2_b64 vcc, exec, s[0:1]
	s_cbranch_vccnz .LBB0_76
	ds_read_b128 v[114:117], v220 offset:57344
	ds_read_b128 v[110:113], v221 offset:57344
	v_add_co_u32_e32 v34, vcc, 0x2000, v34
	s_nop 1
	v_addc_co_u32_e32 v35, vcc, 0, v35, vcc
	ds_read_b128 v[122:125], v220 offset:61440
	ds_read_b128 v[118:121], v221 offset:61440
.LBB0_76:
	s_waitcnt lgkmcnt(0)
	v_mfma_f32_32x32x16_bf16 v[50:65], v[30:33], v[98:101], 0
	s_and_b64 vcc, exec, s[42:43]
	v_mfma_f32_32x32x16_bf16 v[50:65], v[22:25], v[86:89], v[50:65]
	v_mfma_f32_32x32x16_bf16 v[50:65], v[18:21], v[82:85], v[50:65]
	s_waitcnt vmcnt(8)
	v_mfma_f32_32x32x16_bf16 v[50:65], v[26:29], v[90:93], v[50:65]
	s_cbranch_vccnz .LBB0_112
	v_mfma_f32_32x32x16_bf16 v[34:49], v[2:5], v[98:101], 0
	v_mfma_f32_32x32x16_bf16 v[34:49], v[6:9], v[86:89], v[34:49]
	v_mfma_f32_32x32x16_bf16 v[34:49], v[10:13], v[82:85], v[34:49]
	v_mfma_f32_32x32x16_bf16 v[34:49], v[14:17], v[90:93], v[34:49]
	s_and_b64 vcc, exec, s[40:41]
	s_cbranch_vccz .LBB0_113
